# v14 plus nt cache policy on the once-read q/k/decay row loads of GLA pass 1 (P2)
# baseline (speedup 1.0000x reference)
.LBB0_563:
	s_or_b64 exec, exec, s[8:9]
	s_mul_i32 s5, s4, s3
	s_sub_i32 s5, 0x804, s5
	s_add_i32 s8, s4, 1
	s_sub_i32 s9, s5, s3
	s_cmp_ge_u32 s5, s3
	s_cselect_b32 s4, s8, s4
	s_cselect_b32 s5, s9, s5
	s_add_i32 s8, s4, 1
	s_cmp_ge_u32 s5, s3
	s_cselect_b32 s3, s8, s4
	s_xor_b32 s3, s3, s45
	s_sub_i32 s3, s3, s45
	s_mul_i32 s4, s3, s44
	s_sub_i32 s5, 0x804, s4
	s_add_i32 s4, s4, s2
	s_cmp_lt_i32 s2, s5
	s_cselect_b32 s4, s4, -1
	s_not_b32 s5, s4
	s_lshr_b32 s5, s5, 31
	s_add_i32 s5, s3, s5
	s_add_u32 s40, s38, 0x6200000
	s_addc_u32 s41, s39, 0
	s_cmp_lt_i32 s5, 1
	v_ashrrev_i32_e32 v180, 3, v181
	s_waitcnt vmcnt(0) lgkmcnt(0)
	s_barrier
	s_cbranch_scc1 .LBB0_606
	s_mul_i32 s48, s3, s2
	s_cmp_gt_i32 s3, 0
	s_cselect_b32 s12, s48, s4
	s_cmpk_lt_i32 s12, 0x800
	s_cselect_b64 s[10:11], -1, 0
	v_and_b32_e32 v0, 7, v181
	s_and_b64 s[8:9], s[10:11], exec
	v_lshlrev_b32_e32 v1, 3, v0
	v_lshlrev_b32_e32 v0, 4, v0
	s_cselect_b32 s8, 64, 16
	s_mov_b32 s43, 0
	v_mov_b32_e32 v161, 0
	v_cmp_gt_i32_e32 vcc, s8, v180
	v_lshlrev_b32_e32 v162, 1, v1
	v_lshlrev_b32_e32 v164, 1, v0
	v_mov_b32_e32 v16, 0
	v_mov_b32_e32 v17, 0
	v_mov_b32_e32 v18, 0
	v_mov_b32_e32 v19, 0
	v_mov_b32_e32 v20, 0
	v_mov_b32_e32 v21, 0
	v_mov_b32_e32 v22, 0
	v_mov_b32_e32 v23, 0
	v_mov_b32_e32 v24, 0
	v_mov_b32_e32 v25, 0
	v_mov_b32_e32 v26, 0
	v_mov_b32_e32 v27, 0
	v_mov_b32_e32 v28, 0
	v_mov_b32_e32 v29, 0
	v_mov_b32_e32 v30, 0
	v_mov_b32_e32 v31, 0
	v_mov_b32_e32 v32, 0
	v_mov_b32_e32 v33, 0
	v_mov_b32_e32 v34, 0
	v_mov_b32_e32 v35, 0
	v_mov_b32_e32 v36, 0
	v_mov_b32_e32 v37, 0
	v_mov_b32_e32 v38, 0
	v_mov_b32_e32 v39, 0
	s_and_saveexec_b64 s[8:9], vcc
	s_cbranch_execz .LBB0_566
	s_lshl_b32 s14, s12, 4
	s_lshl_b32 s15, s12, 6
	s_and_b32 s14, s14, 0xfffff800
	s_and_b32 s15, s15, 0x7c0
	s_add_i32 s13, s12, 0xfffff800
	s_or_b32 s14, s14, s15
	s_bfe_u32 s12, s12, 0x20005
	s_and_b64 s[10:11], s[10:11], exec
	s_cselect_b32 s10, s14, 0x8200
	v_add_u32_e32 v2, s10, v180
	s_movk_i32 s10, 0x1200
	v_mov_b64_e32 v[0:1], s[40:41]
	s_cselect_b32 s12, s12, s13
	v_mad_i64_i32 v[0:1], s[10:11], v2, s10, v[0:1]
	s_lshl_b32 s10, s12, 6
	s_mov_b32 s11, 0
	v_lshl_add_u64 v[2:3], s[10:11], 1, v[0:1]
	s_lshl_b32 s10, s12, 7
	global_load_dwordx4 v[16:19], v[0:1], off offset:3904 nt
	global_load_dwordx4 v[20:23], v[0:1], off offset:3920 nt
	v_mov_b32_e32 v163, v161
	v_lshl_add_u64 v[0:1], s[10:11], 1, v[0:1]
	v_mov_b32_e32 v165, v161
	v_lshl_add_u64 v[2:3], v[2:3], 0, v[162:163]
	v_lshl_add_u64 v[0:1], v[0:1], 0, v[164:165]
	global_load_dwordx4 v[24:27], v[2:3], off nt
	global_load_dwordx4 v[28:31], v[2:3], off offset:512 nt
	global_load_dwordx4 v[32:35], v[0:1], off offset:1024
	global_load_dwordx4 v[36:39], v[0:1], off offset:1040

.LBB0_597:
	v_cmp_gt_i32_e32 vcc, s30, v180
	v_mov_b32_e32 v19, 0
	v_mov_b32_e32 v18, 0
	v_mov_b32_e32 v17, 0
	v_mov_b32_e32 v16, 0
	v_mov_b32_e32 v23, 0
	v_mov_b32_e32 v22, 0
	v_mov_b32_e32 v21, 0
	v_mov_b32_e32 v20, 0
	v_mov_b32_e32 v27, 0
	v_mov_b32_e32 v26, 0
	v_mov_b32_e32 v25, 0
	v_mov_b32_e32 v24, 0
	v_mov_b32_e32 v31, 0
	v_mov_b32_e32 v30, 0
	v_mov_b32_e32 v29, 0
	v_mov_b32_e32 v28, 0
	v_mov_b32_e32 v35, 0
	v_mov_b32_e32 v34, 0
	v_mov_b32_e32 v33, 0
	v_mov_b32_e32 v32, 0
	v_mov_b32_e32 v39, 0
	v_mov_b32_e32 v38, 0
	v_mov_b32_e32 v37, 0
	v_mov_b32_e32 v36, 0
	s_and_saveexec_b64 s[30:31], vcc
	s_cbranch_execz .LBB0_599
	v_add_u32_e32 v2, s42, v180
	v_mov_b64_e32 v[0:1], s[40:41]
	v_mad_i64_i32 v[0:1], s[46:47], v2, s74, v[0:1]
	s_lshl_b32 s42, s35, 6
	v_lshl_add_u64 v[2:3], s[42:43], 1, v[0:1]
	s_lshl_b32 s42, s35, 7
	global_load_dwordx4 v[20:23], v[0:1], off offset:3920 nt
	global_load_dwordx4 v[16:19], v[0:1], off offset:3904 nt
	v_mov_b32_e32 v163, v161
	v_lshl_add_u64 v[0:1], s[42:43], 1, v[0:1]
	v_mov_b32_e32 v165, v161
	v_lshl_add_u64 v[2:3], v[2:3], 0, v[162:163]
	v_lshl_add_u64 v[0:1], v[0:1], 0, v[164:165]
	global_load_dwordx4 v[24:27], v[2:3], off nt
	global_load_dwordx4 v[28:31], v[2:3], off offset:512 nt
	global_load_dwordx4 v[36:39], v[0:1], off offset:1040
	global_load_dwordx4 v[32:35], v[0:1], off offset:1024
